# per-XCD work queues for the lru2/sg loop (8 counters, item = local*8 + xcd; sg items of one weight group stay on one XCD)
# baseline (speedup 1.0000x reference)
; DI int pop_item(int* ctr, int* slot) {
;   __syncthreads();
;   if (threadIdx.x == 0) *slot = atomicAdd(ctr, 1);
;   __syncthreads();
; __global__ void __launch_bounds__(256, 2) hybrid_fwd(Params p) {
;     ...
;         for (;;) {
;           const int it = pop_item(ctr2, &slot);
.LBB0_774:
	s_barrier
	s_and_saveexec_b64 s[0:1], s[26:27]
	s_cbranch_execz .LBB0_778
	s_mov_b64 s[4:5], exec
	v_mbcnt_lo_u32_b32 v0, s4, 0
	v_mbcnt_hi_u32_b32 v0, s5, v0
	v_cmp_eq_u32_e32 vcc, 0, v0
	s_and_saveexec_b64 s[2:3], vcc
	s_cbranch_execz .LBB0_777
	s_bcnt1_i32_b64 s4, s[4:5]
	v_mov_b32_e32 v2, s4
	v_readlane_b32 s4, v253, 36
	s_and_b32 s4, s4, 7
	s_lshl_b32 s4, s4, 4
	s_add_i32 s4, s4, 16
	v_mov_b32_e32 v4, s4
	v_readlane_b32 s4, v254, 7
	v_readlane_b32 s5, v254, 8
	s_nop 4
	global_atomic_add v2, v4, v2, s[4:5] sc0

; DI int TID() { int t = threadIdx.x; asm volatile("" : "+v"(t)); return t; }
; DI void sg_item(const Params& p, int l, int item, char* lds, int dry) {
;   const int g = item & 7, chunk = (item >> 3) & 31, b = item >> 8;
;   u16* vn = (u16*)lds;
;   const int tid = TID(), lane = tid & 63, w = tid >> 6, r = lane & 31, h = lane >> 5;
;   const size_t tokbase = (size_t)b * S_ + chunk * 128;
; #pragma unroll
;   for (int i = 0; i < 4; ++i) {
;     const int id = tid + 256 * i, row = id >> 3, c = id & 7;
;     *(uint4*)(vn + row * 72 + c * 8) = *(const uint4*)(p.z + (tokbase + row) * ZS + VD + g * 64 + c * 8);
;   }
;   __syncthreads();
;   const int t = 32 * w + r;
;   const float* wr = p.w_spatial + (((size_t)(l * 8 + g) * 128) + t) * 128;
;   const int q4 = (lane & 15) >> 2, p4 = lane & 3, blk = (lane >> 4) & 1;
;   f32x16 acc[2];
; #pragma unroll
;   for (int i = 0; i < 16; ++i) { acc[0][i] = 0.f; acc[1][i] = 0.f; }
;   const int nks = 2 * (w + 1);
;   for (int ks = 0; ks < nks; ++ks) {
; __global__ void __launch_bounds__(256, 2) hybrid_fwd(Params p) {
;     ...
;           const int it = pop_item(ctr2, &slot);
;           if (it >= 3072) break;
;           if (it < 2048) { if (!dry || (P3_MASK & 4)) lru_item(p, l, it, 2, lds, dry); }
;           else { if (!dry || (P3_MASK & 8)) sg_item(p, l, it - 2048, lds, dry); }
.LBB0_778:
	s_or_b64 exec, exec, s[0:1]
	s_waitcnt lgkmcnt(0)
	s_barrier
	ds_read_b32 v0, v221
	s_movk_i32 s0, 0x17f
	s_waitcnt lgkmcnt(0)
	v_cmp_lt_i32_e32 vcc, s0, v0
	v_readfirstlane_b32 s5, v0
	s_mov_b64 s[0:1], -1
	s_cbranch_vccnz .LBB0_773
	v_readlane_b32 s4, v253, 36
	s_and_b32 s4, s4, 7
	s_lshl_b32 s5, s5, 3
	s_or_b32 s5, s5, s4
	s_and_b32 s4, s5, 7
	s_lshl_b32 s6, s4, 6
	s_cmpk_gt_i32 s5, 0x7ff
	s_cbranch_scc0 .LBB0_913
	v_mov_b32_e32 v38, v209
	s_lshl_b32 s0, s5, 4
	v_readlane_b32 s80, v253, 12
	s_and_b32 s7, s0, 0x3f80
	v_ashrrev_i32_e32 v4, 3, v38
	v_readlane_b32 s86, v253, 18
	v_readlane_b32 s87, v253, 19
	v_add_u32_e32 v2, s7, v4
	v_lshlrev_b32_e32 v0, 4, v38
	v_mov_b64_e32 v[6:7], s[86:87]
	v_mad_i64_i32 v[2:3], s[0:1], v2, s75, v[6:7]
	s_lshl_b32 s18, s6, 1
	v_and_b32_e32 v0, 0x70, v0
	v_lshl_add_u64 v[2:3], v[2:3], 0, s[18:19]
	v_lshl_add_u64 v[2:3], v[2:3], 0, v[0:1]
	s_movk_i32 s2, 0x2000
	v_add_co_u32_e32 v2, vcc, s2, v2
	v_mad_u64_u32 v[8:9], s[0:1], v4, s76, v[0:1]
	v_mov_b32_e32 v244, v8
	s_nop 0
	v_addc_co_u32_e32 v3, vcc, 0, v3, vcc
	global_load_dwordx4 v[228:231], v[2:3], off offset:2560
	v_ashrrev_i32_e32 v34, 6, v38
	v_and_b32_e32 v39, 31, v38
	v_lshlrev_b32_e32 v40, 5, v34
	v_bfe_u32 v37, v38, 5, 1
	v_mov_b32_e32 v33, 0
	s_movk_i32 s96, 0x2000
	s_waitcnt vmcnt(32)
	v_or_b32_e32 v36, v40, v39
	s_lshl_b32 s9, s4, 7
	v_mov_b32_e32 v32, v33
	v_mov_b32_e32 v31, v33
	v_mov_b32_e32 v30, v33
	v_mov_b32_e32 v29, v33
	v_mov_b32_e32 v28, v33
	v_mov_b32_e32 v27, v33
	v_mov_b32_e32 v26, v33
	v_mov_b32_e32 v25, v33
	v_mov_b32_e32 v24, v33
	v_mov_b32_e32 v23, v33
	v_mov_b32_e32 v22, v33
	v_mov_b32_e32 v21, v33
	v_mov_b32_e32 v20, v33
	v_mov_b32_e32 v19, v33
	v_mov_b32_e32 v18, v33
	v_mov_b32_e32 v17, v33
	v_mov_b32_e32 v16, v33
	v_mov_b32_e32 v15, v33
	v_mov_b32_e32 v14, v33
	v_mov_b32_e32 v13, v33
	v_mov_b32_e32 v12, v33
	v_mov_b32_e32 v11, v33
	v_mov_b32_e32 v10, v33
	v_readlane_b32 s81, v253, 13
	v_readlane_b32 s82, v253, 14
	v_readlane_b32 s83, v253, 15
	v_readlane_b32 s84, v253, 16
	v_readlane_b32 s85, v253, 17
	v_readlane_b32 s88, v253, 20
	v_readlane_b32 s89, v253, 21
	v_readlane_b32 s90, v253, 22
	v_readlane_b32 s91, v253, 23
	v_readlane_b32 s92, v253, 24
	v_readlane_b32 s93, v253, 25
	v_readlane_b32 s94, v253, 26
	v_readlane_b32 s95, v253, 27
	v_add_u32_e32 v2, 0x100, v38
	v_ashrrev_i32_e32 v4, 3, v2
	v_add_u32_e32 v2, s7, v4
	v_mad_i64_i32 v[2:3], s[0:1], v2, s75, v[6:7]
	v_lshl_add_u64 v[2:3], v[2:3], 0, s[18:19]
	v_lshl_add_u64 v[2:3], v[2:3], 0, v[0:1]
	v_add_co_u32_e32 v2, vcc, s2, v2
	v_mad_u64_u32 v[8:9], s[0:1], v4, s76, v[0:1]
	v_mov_b32_e32 v245, v8
	s_nop 0
	v_addc_co_u32_e32 v3, vcc, 0, v3, vcc
	global_load_dwordx4 v[232:235], v[2:3], off offset:2560
	v_add_u32_e32 v2, 0x200, v38
	v_ashrrev_i32_e32 v4, 3, v2
	v_add_u32_e32 v2, s7, v4
	v_mad_i64_i32 v[2:3], s[0:1], v2, s75, v[6:7]
	v_lshl_add_u64 v[2:3], v[2:3], 0, s[18:19]
	v_lshl_add_u64 v[2:3], v[2:3], 0, v[0:1]
	v_add_co_u32_e32 v2, vcc, s2, v2
	v_mad_u64_u32 v[8:9], s[0:1], v4, s76, v[0:1]
	v_mov_b32_e32 v246, v8
	s_nop 0
	v_addc_co_u32_e32 v3, vcc, 0, v3, vcc
	global_load_dwordx4 v[236:239], v[2:3], off offset:2560
	v_mov_b32_e32 v9, v33
	v_add_u32_e32 v2, 0x300, v38
	v_ashrrev_i32_e32 v4, 3, v2
	v_add_u32_e32 v2, s7, v4
	v_mad_i64_i32 v[2:3], s[0:1], v2, s75, v[6:7]
	v_lshl_add_u64 v[2:3], v[2:3], 0, s[18:19]
	v_lshl_add_u64 v[2:3], v[2:3], 0, v[0:1]
	v_add_co_u32_e32 v2, vcc, s2, v2
	v_mad_u64_u32 v[6:7], s[0:1], v4, s76, v[0:1]
	s_nop 0
	v_addc_co_u32_e32 v3, vcc, 0, v3, vcc
	global_load_dwordx4 v[240:243], v[2:3], off offset:2560
	v_cmp_lt_i32_e32 vcc, -1, v34
	v_lshlrev_b32_e32 v0, 3, v37
	v_mov_b32_e32 v8, v33
	v_mov_b32_e32 v7, v33
	s_waitcnt vmcnt(3)
	ds_write_b128 v244, v[228:231]
	s_waitcnt vmcnt(2)
	ds_write_b128 v245, v[232:235]
	s_waitcnt vmcnt(1)
	ds_write_b128 v246, v[236:239]
	s_waitcnt vmcnt(0)
	ds_write_b128 v6, v[240:243]
	v_mov_b32_e32 v6, v33
	v_mov_b32_e32 v5, v33
	v_mov_b32_e32 v4, v33
	v_mov_b32_e32 v3, v33
	v_mov_b32_e32 v2, v33
	s_waitcnt lgkmcnt(0)
	s_barrier
	s_and_saveexec_b64 s[0:1], vcc
	s_cbranch_execz .LBB0_784
	v_bfe_u32 v2, v38, 2, 2
	v_lshlrev_b32_e32 v4, 1, v38
	v_mul_u32_u24_e32 v3, 0x480, v37
	v_mul_u32_u24_e32 v2, 0x90, v2
	v_and_b32_e32 v4, 32, v4
	v_add3_u32 v2, v3, v2, v4
	v_and_b32_e32 v3, 3, v38
	v_lshlrev_b32_e32 v3, 3, v3
	s_movk_i32 s2, 0x280
	v_add3_u32 v37, v2, v3, s2
	v_add_u32_e32 v2, v40, v39
	v_ashrrev_i32_e32 v3, 31, v2
	s_add_i32 s2, s8, s9
	s_mov_b32 s3, s19
	v_lshl_add_u64 v[2:3], v[2:3], 0, s[2:3]
	v_lshlrev_b64 v[2:3], 9, v[2:3]
	v_readlane_b32 s2, v253, 32
	v_and_or_b32 v2, v38, 32, v2
	v_readlane_b32 s3, v253, 33
	v_mov_b32_e32 v35, v36
	v_lshl_add_u32 v34, v34, 1, 2
	v_lshl_add_u64 v[38:39], s[2:3], 0, v[2:3]
	v_mov_b32_e32 v2, 0
	s_mov_b64 s[2:3], 0
	v_mov_b32_e32 v40, v0
	v_mov_b32_e32 v3, v2
	v_mov_b32_e32 v4, v2
	v_mov_b32_e32 v5, v2
	v_mov_b32_e32 v6, v2
	v_mov_b32_e32 v7, v2
	v_mov_b32_e32 v8, v2
	v_mov_b32_e32 v9, v2
	v_mov_b32_e32 v10, v2
	v_mov_b32_e32 v11, v2
	v_mov_b32_e32 v12, v2
	v_mov_b32_e32 v13, v2
	v_mov_b32_e32 v14, v2
	v_mov_b32_e32 v15, v2
	v_mov_b32_e32 v16, v2
	v_mov_b32_e32 v17, v2
	v_mov_b32_e32 v18, v2
	v_mov_b32_e32 v19, v2
	v_mov_b32_e32 v20, v2
	v_mov_b32_e32 v21, v2
	v_mov_b32_e32 v22, v2
	v_mov_b32_e32 v23, v2
	v_mov_b32_e32 v24, v2
	v_mov_b32_e32 v25, v2
	v_mov_b32_e32 v26, v2
	v_mov_b32_e32 v27, v2
	v_mov_b32_e32 v28, v2
	v_mov_b32_e32 v29, v2
	v_mov_b32_e32 v30, v2
	v_mov_b32_e32 v31, v2
	v_mov_b32_e32 v32, v2
	v_mov_b32_e32 v33, v2
	s_mov_b32 s10, 0x5040100
	global_load_dwordx4 v[96:99], v[38:39], off offset:-16
	global_load_dwordx4 v[100:103], v[38:39], off
	global_load_dwordx4 v[104:107], v[38:39], off offset:48
	global_load_dwordx4 v[108:111], v[38:39], off offset:64
	global_load_dwordx4 v[112:115], v[38:39], off offset:112
	global_load_dwordx4 v[116:119], v[38:39], off offset:128
	global_load_dwordx4 v[120:123], v[38:39], off offset:176
	global_load_dwordx4 v[124:127], v[38:39], off offset:192
	global_load_dwordx4 v[128:131], v[38:39], off offset:240
	global_load_dwordx4 v[132:135], v[38:39], off offset:256
	global_load_dwordx4 v[136:139], v[38:39], off offset:304
	global_load_dwordx4 v[140:143], v[38:39], off offset:320
	global_load_dwordx4 v[144:147], v[38:39], off offset:368
	global_load_dwordx4 v[148:151], v[38:39], off offset:384
	global_load_dwordx4 v[152:155], v[38:39], off offset:432
	global_load_dwordx4 v[156:159], v[38:39], off offset:448
